# norm phase split into two pipelined token groups so first-group stores overlap second-group loads
# speedup vs baseline: 1.0337x; 1.0020x over previous
.Lnorm_x0:
	s_lshl_b32 s24, s10, 12
	s_add_u32 s26, s20, s24
	s_addc_u32 s27, s21, 0
	global_load_dwordx4 v[66:69], v0, s[26:27]
	global_load_dwordx4 v[70:73], v0, s[26:27] offset:1024
	global_load_dwordx4 v[74:77], v0, s[26:27] offset:2048
	global_load_dwordx4 v[78:81], v0, s[26:27] offset:3072
	s_add_u32 s26, s20, s24
	s_addc_u32 s27, s21, 0
	s_add_u32 s26, s26, 0x800000
	s_addc_u32 s27, s27, 0
	global_load_dwordx4 v[82:85], v0, s[26:27]
	global_load_dwordx4 v[86:89], v0, s[26:27] offset:1024
	global_load_dwordx4 v[90:93], v0, s[26:27] offset:2048
	global_load_dwordx4 v[94:97], v0, s[26:27] offset:3072
	s_add_u32 s26, s20, s24
	s_addc_u32 s27, s21, 0
	s_add_u32 s26, s26, 0x1000000
	s_addc_u32 s27, s27, 0
	global_load_dwordx4 v[98:101], v0, s[26:27]
	global_load_dwordx4 v[102:105], v0, s[26:27] offset:1024
	global_load_dwordx4 v[106:109], v0, s[26:27] offset:2048
	global_load_dwordx4 v[110:113], v0, s[26:27] offset:3072
	global_load_dwordx4 v[2:5], v0, s[12:13]
	global_load_dwordx4 v[6:9], v0, s[12:13] offset:1024
	global_load_dwordx4 v[10:13], v0, s[12:13] offset:2048
	global_load_dwordx4 v[14:17], v0, s[12:13] offset:3072
	s_add_u32 s30, s16, 0x1000
	s_addc_u32 s31, s17, 0
	global_load_dwordx4 v[18:21], v0, s[16:17]
	global_load_dwordx4 v[22:25], v0, s[16:17] offset:1024
	global_load_dwordx4 v[26:29], v0, s[16:17] offset:2048
	global_load_dwordx4 v[30:33], v0, s[16:17] offset:3072
	global_load_dwordx4 v[34:37], v0, s[30:31]
	global_load_dwordx4 v[38:41], v0, s[30:31] offset:1024
	global_load_dwordx4 v[42:45], v0, s[30:31] offset:2048
	global_load_dwordx4 v[46:49], v0, s[30:31] offset:3072
	s_add_u32 s26, s20, s24
	s_addc_u32 s27, s21, 0
	s_add_u32 s26, s26, 0x1800000
	s_addc_u32 s27, s27, 0
	global_load_dwordx4 v[114:117], v0, s[26:27]
	global_load_dwordx4 v[118:121], v0, s[26:27] offset:1024
	global_load_dwordx4 v[122:125], v0, s[26:27] offset:2048
	global_load_dwordx4 v[126:129], v0, s[26:27] offset:3072
	s_add_u32 s26, s22, s24
	s_addc_u32 s27, s23, 0
	s_add_u32 s26, s26, 0x2000000
	s_addc_u32 s27, s27, 0
	global_load_dwordx4 v[130:133], v0, s[26:27]
	global_load_dwordx4 v[134:137], v0, s[26:27] offset:1024
	global_load_dwordx4 v[138:141], v0, s[26:27] offset:2048
	global_load_dwordx4 v[142:145], v0, s[26:27] offset:3072
	s_add_u32 s26, s22, s24
	s_addc_u32 s27, s23, 0
	s_add_u32 s26, s26, 0x2800000
	s_addc_u32 s27, s27, 0
	global_load_dwordx4 v[146:149], v0, s[26:27]
	global_load_dwordx4 v[150:153], v0, s[26:27] offset:1024
	global_load_dwordx4 v[154:157], v0, s[26:27] offset:2048
	global_load_dwordx4 v[158:161], v0, s[26:27] offset:3072
	s_add_u32 s36, s16, 0x3000
	s_addc_u32 s37, s17, 0
	s_add_u32 s30, s16, 0x4000
	s_addc_u32 s31, s17, 0
	global_load_dwordx4 v[200:203], v0, s[36:37]
	global_load_dwordx4 v[204:207], v0, s[36:37] offset:1024
	global_load_dwordx4 v[208:211], v0, s[36:37] offset:2048
	global_load_dwordx4 v[212:215], v0, s[36:37] offset:3072
	global_load_dwordx4 v[232:235], v0, s[30:31]
	global_load_dwordx4 v[236:239], v0, s[30:31] offset:1024
	global_load_dwordx4 v[240:243], v0, s[30:31] offset:2048
	global_load_dwordx4 v[244:247], v0, s[30:31] offset:3072
	s_lshl_b32 s25, s10, 11
	s_waitcnt vmcnt(20)
	v_pk_mul_f32 v[50:51], v[66:67], v[66:67]
	v_pk_mul_f32 v[52:53], v[82:83], v[82:83]
	v_pk_mul_f32 v[54:55], v[98:99], v[98:99]
	v_pk_fma_f32 v[50:51], v[68:69], v[68:69], v[50:51]
	v_pk_fma_f32 v[52:53], v[84:85], v[84:85], v[52:53]
	v_pk_fma_f32 v[54:55], v[100:101], v[100:101], v[54:55]
	v_pk_fma_f32 v[50:51], v[70:71], v[70:71], v[50:51]
	v_pk_fma_f32 v[52:53], v[86:87], v[86:87], v[52:53]
	v_pk_fma_f32 v[54:55], v[102:103], v[102:103], v[54:55]
	v_pk_fma_f32 v[50:51], v[72:73], v[72:73], v[50:51]
	v_pk_fma_f32 v[52:53], v[88:89], v[88:89], v[52:53]
	v_pk_fma_f32 v[54:55], v[104:105], v[104:105], v[54:55]
	v_pk_fma_f32 v[50:51], v[74:75], v[74:75], v[50:51]
	v_pk_fma_f32 v[52:53], v[90:91], v[90:91], v[52:53]
	v_pk_fma_f32 v[54:55], v[106:107], v[106:107], v[54:55]
	v_pk_fma_f32 v[50:51], v[76:77], v[76:77], v[50:51]
	v_pk_fma_f32 v[52:53], v[92:93], v[92:93], v[52:53]
	v_pk_fma_f32 v[54:55], v[108:109], v[108:109], v[54:55]
	v_pk_fma_f32 v[50:51], v[78:79], v[78:79], v[50:51]
	v_pk_fma_f32 v[52:53], v[94:95], v[94:95], v[52:53]
	v_pk_fma_f32 v[54:55], v[110:111], v[110:111], v[54:55]
	v_pk_fma_f32 v[50:51], v[80:81], v[80:81], v[50:51]
	v_pk_fma_f32 v[52:53], v[96:97], v[96:97], v[52:53]
	v_pk_fma_f32 v[54:55], v[112:113], v[112:113], v[54:55]
	v_add_f32_e32 v216, v50, v51
	v_add_f32_e32 v217, v52, v53
	v_add_f32_e32 v218, v54, v55
	s_nop 1
	v_add_f32_dpp v216, v216, v216 row_ror:8 row_mask:0xf bank_mask:0xf
	v_add_f32_dpp v217, v217, v217 row_ror:8 row_mask:0xf bank_mask:0xf
	v_add_f32_dpp v218, v218, v218 row_ror:8 row_mask:0xf bank_mask:0xf
	v_add_f32_dpp v216, v216, v216 row_ror:4 row_mask:0xf bank_mask:0xf
	v_add_f32_dpp v217, v217, v217 row_ror:4 row_mask:0xf bank_mask:0xf
	v_add_f32_dpp v218, v218, v218 row_ror:4 row_mask:0xf bank_mask:0xf
	v_add_f32_dpp v216, v216, v216 row_ror:2 row_mask:0xf bank_mask:0xf
	v_add_f32_dpp v217, v217, v217 row_ror:2 row_mask:0xf bank_mask:0xf
	v_add_f32_dpp v218, v218, v218 row_ror:2 row_mask:0xf bank_mask:0xf
	v_add_f32_dpp v216, v216, v216 row_ror:1 row_mask:0xf bank_mask:0xf
	v_add_f32_dpp v217, v217, v217 row_ror:1 row_mask:0xf bank_mask:0xf
	v_add_f32_dpp v218, v218, v218 row_ror:1 row_mask:0xf bank_mask:0xf
	v_mov_b32_e32 v248, v216
	v_mov_b32_e32 v249, v217
	v_mov_b32_e32 v250, v218
	s_nop 1
	v_permlane16_swap_b32 v216, v248
	v_permlane16_swap_b32 v217, v249
	v_permlane16_swap_b32 v218, v250
	v_add_f32_e32 v216, v216, v248
	v_add_f32_e32 v217, v217, v249
	v_add_f32_e32 v218, v218, v250
	v_mov_b32_e32 v248, v216
	v_mov_b32_e32 v249, v217
	v_mov_b32_e32 v250, v218
	s_nop 1
	v_permlane32_swap_b32 v216, v248
	v_permlane32_swap_b32 v217, v249
	v_permlane32_swap_b32 v218, v250
	v_add_f32_e32 v216, v216, v248
	v_add_f32_e32 v217, v217, v249
	v_add_f32_e32 v218, v218, v250
	v_fmamk_f32 v216, v216, 0x3a800000, v177
	v_fmamk_f32 v217, v217, 0x3a800000, v177
	v_fmamk_f32 v218, v218, 0x3a800000, v177
	v_rsq_f32_e32 v50, v216
	v_rsq_f32_e32 v52, v217
	v_rsq_f32_e32 v54, v218
	v_pk_add_f32 v[34:35], v[34:35], 1.0 op_sel_hi:[1,0]
	v_pk_add_f32 v[36:37], v[36:37], 1.0 op_sel_hi:[1,0]
	v_pk_add_f32 v[38:39], v[38:39], 1.0 op_sel_hi:[1,0]
	v_pk_add_f32 v[40:41], v[40:41], 1.0 op_sel_hi:[1,0]
	v_pk_add_f32 v[42:43], v[42:43], 1.0 op_sel_hi:[1,0]
	v_pk_add_f32 v[44:45], v[44:45], 1.0 op_sel_hi:[1,0]
	v_pk_add_f32 v[46:47], v[46:47], 1.0 op_sel_hi:[1,0]
	v_pk_add_f32 v[48:49], v[48:49], 1.0 op_sel_hi:[1,0]
	s_add_u32 s4, s88, s25
	s_addc_u32 s5, s89, 0
	v_pk_mul_f32 v[66:67], v[66:67], v[50:51] op_sel_hi:[1,0]
	v_pk_mul_f32 v[68:69], v[68:69], v[50:51] op_sel_hi:[1,0]
	v_pk_mul_f32 v[66:67], v[2:3], v[66:67]
	v_pk_mul_f32 v[68:69], v[4:5], v[68:69]
	v_pk_fma_f32 v[66:67], v[34:35], v[66:67], v[18:19]
	v_pk_fma_f32 v[68:69], v[36:37], v[68:69], v[20:21]
	v_cvt_pk_bf16_f32 v66, v66, v67
	v_cvt_pk_bf16_f32 v67, v68, v69
	global_store_dwordx2 v1, v[66:67], s[4:5]
	v_pk_mul_f32 v[70:71], v[70:71], v[50:51] op_sel_hi:[1,0]
	v_pk_mul_f32 v[72:73], v[72:73], v[50:51] op_sel_hi:[1,0]
	v_pk_mul_f32 v[70:71], v[6:7], v[70:71]
	v_pk_mul_f32 v[72:73], v[8:9], v[72:73]
	v_pk_fma_f32 v[70:71], v[38:39], v[70:71], v[22:23]
	v_pk_fma_f32 v[72:73], v[40:41], v[72:73], v[24:25]
	v_cvt_pk_bf16_f32 v70, v70, v71
	v_cvt_pk_bf16_f32 v71, v72, v73
	global_store_dwordx2 v1, v[70:71], s[4:5] offset:512
	v_pk_mul_f32 v[74:75], v[74:75], v[50:51] op_sel_hi:[1,0]
	v_pk_mul_f32 v[76:77], v[76:77], v[50:51] op_sel_hi:[1,0]
	v_pk_mul_f32 v[74:75], v[10:11], v[74:75]
	v_pk_mul_f32 v[76:77], v[12:13], v[76:77]
	v_pk_fma_f32 v[74:75], v[42:43], v[74:75], v[26:27]
	v_pk_fma_f32 v[76:77], v[44:45], v[76:77], v[28:29]
	v_cvt_pk_bf16_f32 v74, v74, v75
	v_cvt_pk_bf16_f32 v75, v76, v77
	global_store_dwordx2 v1, v[74:75], s[4:5] offset:1024
	v_pk_mul_f32 v[78:79], v[78:79], v[50:51] op_sel_hi:[1,0]
	v_pk_mul_f32 v[80:81], v[80:81], v[50:51] op_sel_hi:[1,0]
	v_pk_mul_f32 v[78:79], v[14:15], v[78:79]
	v_pk_mul_f32 v[80:81], v[16:17], v[80:81]
	v_pk_fma_f32 v[78:79], v[46:47], v[78:79], v[30:31]
	v_pk_fma_f32 v[80:81], v[48:49], v[80:81], v[32:33]
	v_cvt_pk_bf16_f32 v78, v78, v79
	v_cvt_pk_bf16_f32 v79, v80, v81
	global_store_dwordx2 v1, v[78:79], s[4:5] offset:1536
	s_add_u32 s4, s88, s25
	s_addc_u32 s5, s89, 0
	s_add_u32 s4, s4, 0x400000
	s_addc_u32 s5, s5, 0
	v_pk_mul_f32 v[82:83], v[82:83], v[52:53] op_sel_hi:[1,0]
	v_pk_mul_f32 v[84:85], v[84:85], v[52:53] op_sel_hi:[1,0]
	v_pk_mul_f32 v[82:83], v[2:3], v[82:83]
	v_pk_mul_f32 v[84:85], v[4:5], v[84:85]
	v_pk_fma_f32 v[82:83], v[34:35], v[82:83], v[18:19]
	v_pk_fma_f32 v[84:85], v[36:37], v[84:85], v[20:21]
	v_cvt_pk_bf16_f32 v82, v82, v83
	v_cvt_pk_bf16_f32 v83, v84, v85
	global_store_dwordx2 v1, v[82:83], s[4:5]
	v_pk_mul_f32 v[86:87], v[86:87], v[52:53] op_sel_hi:[1,0]
	v_pk_mul_f32 v[88:89], v[88:89], v[52:53] op_sel_hi:[1,0]
	v_pk_mul_f32 v[86:87], v[6:7], v[86:87]
	v_pk_mul_f32 v[88:89], v[8:9], v[88:89]
	v_pk_fma_f32 v[86:87], v[38:39], v[86:87], v[22:23]
	v_pk_fma_f32 v[88:89], v[40:41], v[88:89], v[24:25]
	v_cvt_pk_bf16_f32 v86, v86, v87
	v_cvt_pk_bf16_f32 v87, v88, v89
	global_store_dwordx2 v1, v[86:87], s[4:5] offset:512
	v_pk_mul_f32 v[90:91], v[90:91], v[52:53] op_sel_hi:[1,0]
	v_pk_mul_f32 v[92:93], v[92:93], v[52:53] op_sel_hi:[1,0]
	v_pk_mul_f32 v[90:91], v[10:11], v[90:91]
	v_pk_mul_f32 v[92:93], v[12:13], v[92:93]
	v_pk_fma_f32 v[90:91], v[42:43], v[90:91], v[26:27]
	v_pk_fma_f32 v[92:93], v[44:45], v[92:93], v[28:29]
	v_cvt_pk_bf16_f32 v90, v90, v91
	v_cvt_pk_bf16_f32 v91, v92, v93
	global_store_dwordx2 v1, v[90:91], s[4:5] offset:1024
	v_pk_mul_f32 v[94:95], v[94:95], v[52:53] op_sel_hi:[1,0]
	v_pk_mul_f32 v[96:97], v[96:97], v[52:53] op_sel_hi:[1,0]
	v_pk_mul_f32 v[94:95], v[14:15], v[94:95]
	v_pk_mul_f32 v[96:97], v[16:17], v[96:97]
	v_pk_fma_f32 v[94:95], v[46:47], v[94:95], v[30:31]
	v_pk_fma_f32 v[96:97], v[48:49], v[96:97], v[32:33]
	v_cvt_pk_bf16_f32 v94, v94, v95
	v_cvt_pk_bf16_f32 v95, v96, v97
	global_store_dwordx2 v1, v[94:95], s[4:5] offset:1536
	s_add_u32 s4, s88, s25
	s_addc_u32 s5, s89, 0
	s_add_u32 s4, s4, 0x800000
	s_addc_u32 s5, s5, 0
	v_pk_mul_f32 v[98:99], v[98:99], v[54:55] op_sel_hi:[1,0]
	v_pk_mul_f32 v[100:101], v[100:101], v[54:55] op_sel_hi:[1,0]
	v_pk_mul_f32 v[98:99], v[2:3], v[98:99]
	v_pk_mul_f32 v[100:101], v[4:5], v[100:101]
	v_pk_fma_f32 v[98:99], v[34:35], v[98:99], v[18:19]
	v_pk_fma_f32 v[100:101], v[36:37], v[100:101], v[20:21]
	v_cvt_pk_bf16_f32 v98, v98, v99
	v_cvt_pk_bf16_f32 v99, v100, v101
	global_store_dwordx2 v1, v[98:99], s[4:5]
	v_pk_mul_f32 v[102:103], v[102:103], v[54:55] op_sel_hi:[1,0]
	v_pk_mul_f32 v[104:105], v[104:105], v[54:55] op_sel_hi:[1,0]
	v_pk_mul_f32 v[102:103], v[6:7], v[102:103]
	v_pk_mul_f32 v[104:105], v[8:9], v[104:105]
	v_pk_fma_f32 v[102:103], v[38:39], v[102:103], v[22:23]
	v_pk_fma_f32 v[104:105], v[40:41], v[104:105], v[24:25]
	v_cvt_pk_bf16_f32 v102, v102, v103
	v_cvt_pk_bf16_f32 v103, v104, v105
	global_store_dwordx2 v1, v[102:103], s[4:5] offset:512
	v_pk_mul_f32 v[106:107], v[106:107], v[54:55] op_sel_hi:[1,0]
	v_pk_mul_f32 v[108:109], v[108:109], v[54:55] op_sel_hi:[1,0]
	v_pk_mul_f32 v[106:107], v[10:11], v[106:107]
	v_pk_mul_f32 v[108:109], v[12:13], v[108:109]
	v_pk_fma_f32 v[106:107], v[42:43], v[106:107], v[26:27]
	v_pk_fma_f32 v[108:109], v[44:45], v[108:109], v[28:29]
	v_cvt_pk_bf16_f32 v106, v106, v107
	v_cvt_pk_bf16_f32 v107, v108, v109
	global_store_dwordx2 v1, v[106:107], s[4:5] offset:1024
	v_pk_mul_f32 v[110:111], v[110:111], v[54:55] op_sel_hi:[1,0]
	v_pk_mul_f32 v[112:113], v[112:113], v[54:55] op_sel_hi:[1,0]
	v_pk_mul_f32 v[110:111], v[14:15], v[110:111]
	v_pk_mul_f32 v[112:113], v[16:17], v[112:113]
	v_pk_fma_f32 v[110:111], v[46:47], v[110:111], v[30:31]
	v_pk_fma_f32 v[112:113], v[48:49], v[112:113], v[32:33]
	v_cvt_pk_bf16_f32 v110, v110, v111
	v_cvt_pk_bf16_f32 v111, v112, v113
	global_store_dwordx2 v1, v[110:111], s[4:5] offset:1536
	s_waitcnt vmcnt(12)
	v_pk_mul_f32 v[56:57], v[114:115], v[114:115]
	v_pk_mul_f32 v[58:59], v[130:131], v[130:131]
	v_pk_mul_f32 v[60:61], v[146:147], v[146:147]
	v_pk_fma_f32 v[56:57], v[116:117], v[116:117], v[56:57]
	v_pk_fma_f32 v[58:59], v[132:133], v[132:133], v[58:59]
	v_pk_fma_f32 v[60:61], v[148:149], v[148:149], v[60:61]
	v_pk_fma_f32 v[56:57], v[118:119], v[118:119], v[56:57]
	v_pk_fma_f32 v[58:59], v[134:135], v[134:135], v[58:59]
	v_pk_fma_f32 v[60:61], v[150:151], v[150:151], v[60:61]
	v_pk_fma_f32 v[56:57], v[120:121], v[120:121], v[56:57]
	v_pk_fma_f32 v[58:59], v[136:137], v[136:137], v[58:59]
	v_pk_fma_f32 v[60:61], v[152:153], v[152:153], v[60:61]
	v_pk_fma_f32 v[56:57], v[122:123], v[122:123], v[56:57]
	v_pk_fma_f32 v[58:59], v[138:139], v[138:139], v[58:59]
	v_pk_fma_f32 v[60:61], v[154:155], v[154:155], v[60:61]
	v_pk_fma_f32 v[56:57], v[124:125], v[124:125], v[56:57]
	v_pk_fma_f32 v[58:59], v[140:141], v[140:141], v[58:59]
	v_pk_fma_f32 v[60:61], v[156:157], v[156:157], v[60:61]
	v_pk_fma_f32 v[56:57], v[126:127], v[126:127], v[56:57]
	v_pk_fma_f32 v[58:59], v[142:143], v[142:143], v[58:59]
	v_pk_fma_f32 v[60:61], v[158:159], v[158:159], v[60:61]
	v_pk_fma_f32 v[56:57], v[128:129], v[128:129], v[56:57]
	v_pk_fma_f32 v[58:59], v[144:145], v[144:145], v[58:59]
	v_pk_fma_f32 v[60:61], v[160:161], v[160:161], v[60:61]
	v_add_f32_e32 v219, v56, v57
	v_add_f32_e32 v220, v58, v59
	v_add_f32_e32 v221, v60, v61
	s_nop 1
	v_add_f32_dpp v219, v219, v219 row_ror:8 row_mask:0xf bank_mask:0xf
	v_add_f32_dpp v220, v220, v220 row_ror:8 row_mask:0xf bank_mask:0xf
	v_add_f32_dpp v221, v221, v221 row_ror:8 row_mask:0xf bank_mask:0xf
	v_add_f32_dpp v219, v219, v219 row_ror:4 row_mask:0xf bank_mask:0xf
	v_add_f32_dpp v220, v220, v220 row_ror:4 row_mask:0xf bank_mask:0xf
	v_add_f32_dpp v221, v221, v221 row_ror:4 row_mask:0xf bank_mask:0xf
	v_add_f32_dpp v219, v219, v219 row_ror:2 row_mask:0xf bank_mask:0xf
	v_add_f32_dpp v220, v220, v220 row_ror:2 row_mask:0xf bank_mask:0xf
	v_add_f32_dpp v221, v221, v221 row_ror:2 row_mask:0xf bank_mask:0xf
	v_add_f32_dpp v219, v219, v219 row_ror:1 row_mask:0xf bank_mask:0xf
	v_add_f32_dpp v220, v220, v220 row_ror:1 row_mask:0xf bank_mask:0xf
	v_add_f32_dpp v221, v221, v221 row_ror:1 row_mask:0xf bank_mask:0xf
	v_mov_b32_e32 v251, v219
	v_mov_b32_e32 v62, v220
	v_mov_b32_e32 v63, v221
	s_nop 1
	v_permlane16_swap_b32 v219, v251
	v_permlane16_swap_b32 v220, v62
	v_permlane16_swap_b32 v221, v63
	v_add_f32_e32 v219, v219, v251
	v_add_f32_e32 v220, v220, v62
	v_add_f32_e32 v221, v221, v63
	v_mov_b32_e32 v251, v219
	v_mov_b32_e32 v62, v220
	v_mov_b32_e32 v63, v221
	s_nop 1
	v_permlane32_swap_b32 v219, v251
	v_permlane32_swap_b32 v220, v62
	v_permlane32_swap_b32 v221, v63
	v_add_f32_e32 v219, v219, v251
	v_add_f32_e32 v220, v220, v62
	v_add_f32_e32 v221, v221, v63
	v_fmamk_f32 v219, v219, 0x3a800000, v177
	v_fmamk_f32 v220, v220, 0x3a800000, v177
	v_fmamk_f32 v221, v221, 0x3a800000, v177
	v_rsq_f32_e32 v56, v219
	v_rsq_f32_e32 v58, v220
	v_rsq_f32_e32 v60, v221
	v_pk_add_f32 v[232:233], v[232:233], 1.0 op_sel_hi:[1,0]
	v_pk_add_f32 v[234:235], v[234:235], 1.0 op_sel_hi:[1,0]
	v_pk_add_f32 v[236:237], v[236:237], 1.0 op_sel_hi:[1,0]
	v_pk_add_f32 v[238:239], v[238:239], 1.0 op_sel_hi:[1,0]
	v_pk_add_f32 v[240:241], v[240:241], 1.0 op_sel_hi:[1,0]
	v_pk_add_f32 v[242:243], v[242:243], 1.0 op_sel_hi:[1,0]
	v_pk_add_f32 v[244:245], v[244:245], 1.0 op_sel_hi:[1,0]
	v_pk_add_f32 v[246:247], v[246:247], 1.0 op_sel_hi:[1,0]
	s_add_u32 s4, s88, s25
	s_addc_u32 s5, s89, 0
	s_add_u32 s4, s4, 0xc00000
	s_addc_u32 s5, s5, 0
	v_pk_mul_f32 v[114:115], v[114:115], v[56:57] op_sel_hi:[1,0]
	v_pk_mul_f32 v[116:117], v[116:117], v[56:57] op_sel_hi:[1,0]
	v_pk_mul_f32 v[114:115], v[2:3], v[114:115]
	v_pk_mul_f32 v[116:117], v[4:5], v[116:117]
	v_pk_fma_f32 v[114:115], v[34:35], v[114:115], v[18:19]
	v_pk_fma_f32 v[116:117], v[36:37], v[116:117], v[20:21]
	v_cvt_pk_bf16_f32 v114, v114, v115
	v_cvt_pk_bf16_f32 v115, v116, v117
	global_store_dwordx2 v1, v[114:115], s[4:5]
	v_pk_mul_f32 v[118:119], v[118:119], v[56:57] op_sel_hi:[1,0]
	v_pk_mul_f32 v[120:121], v[120:121], v[56:57] op_sel_hi:[1,0]
	v_pk_mul_f32 v[118:119], v[6:7], v[118:119]
	v_pk_mul_f32 v[120:121], v[8:9], v[120:121]
	v_pk_fma_f32 v[118:119], v[38:39], v[118:119], v[22:23]
	v_pk_fma_f32 v[120:121], v[40:41], v[120:121], v[24:25]
	v_cvt_pk_bf16_f32 v118, v118, v119
	v_cvt_pk_bf16_f32 v119, v120, v121
	global_store_dwordx2 v1, v[118:119], s[4:5] offset:512
	v_pk_mul_f32 v[122:123], v[122:123], v[56:57] op_sel_hi:[1,0]
	v_pk_mul_f32 v[124:125], v[124:125], v[56:57] op_sel_hi:[1,0]
	v_pk_mul_f32 v[122:123], v[10:11], v[122:123]
	v_pk_mul_f32 v[124:125], v[12:13], v[124:125]
	v_pk_fma_f32 v[122:123], v[42:43], v[122:123], v[26:27]
	v_pk_fma_f32 v[124:125], v[44:45], v[124:125], v[28:29]
	v_cvt_pk_bf16_f32 v122, v122, v123
	v_cvt_pk_bf16_f32 v123, v124, v125
	global_store_dwordx2 v1, v[122:123], s[4:5] offset:1024
	v_pk_mul_f32 v[126:127], v[126:127], v[56:57] op_sel_hi:[1,0]
	v_pk_mul_f32 v[128:129], v[128:129], v[56:57] op_sel_hi:[1,0]
	v_pk_mul_f32 v[126:127], v[14:15], v[126:127]
	v_pk_mul_f32 v[128:129], v[16:17], v[128:129]
	v_pk_fma_f32 v[126:127], v[46:47], v[126:127], v[30:31]
	v_pk_fma_f32 v[128:129], v[48:49], v[128:129], v[32:33]
	v_cvt_pk_bf16_f32 v126, v126, v127
	v_cvt_pk_bf16_f32 v127, v128, v129
	global_store_dwordx2 v1, v[126:127], s[4:5] offset:1536
	s_add_u32 s36, s16, 0x6000
	s_addc_u32 s37, s17, 0
	s_add_u32 s30, s16, 0x7000
	s_addc_u32 s31, s17, 0
	global_load_dwordx4 v[18:21], v0, s[36:37]
	global_load_dwordx4 v[22:25], v0, s[36:37] offset:1024
	global_load_dwordx4 v[26:29], v0, s[36:37] offset:2048
	global_load_dwordx4 v[30:33], v0, s[36:37] offset:3072
	global_load_dwordx4 v[34:37], v0, s[30:31]
	global_load_dwordx4 v[38:41], v0, s[30:31] offset:1024
	global_load_dwordx4 v[42:45], v0, s[30:31] offset:2048
	global_load_dwordx4 v[46:49], v0, s[30:31] offset:3072
	s_add_u32 s4, s88, s25
	s_addc_u32 s5, s89, 0
	s_add_u32 s4, s4, 0x1000000
	s_addc_u32 s5, s5, 0
	v_pk_mul_f32 v[130:131], v[130:131], v[58:59] op_sel_hi:[1,0]
	v_pk_mul_f32 v[132:133], v[132:133], v[58:59] op_sel_hi:[1,0]
	v_pk_mul_f32 v[130:131], v[2:3], v[130:131]
	v_pk_mul_f32 v[132:133], v[4:5], v[132:133]
	v_pk_fma_f32 v[130:131], v[232:233], v[130:131], v[200:201]
	v_pk_fma_f32 v[132:133], v[234:235], v[132:133], v[202:203]
	v_cvt_pk_bf16_f32 v130, v130, v131
	v_cvt_pk_bf16_f32 v131, v132, v133
	global_store_dwordx2 v1, v[130:131], s[4:5]
	v_pk_mul_f32 v[134:135], v[134:135], v[58:59] op_sel_hi:[1,0]
	v_pk_mul_f32 v[136:137], v[136:137], v[58:59] op_sel_hi:[1,0]
	v_pk_mul_f32 v[134:135], v[6:7], v[134:135]
	v_pk_mul_f32 v[136:137], v[8:9], v[136:137]
	v_pk_fma_f32 v[134:135], v[236:237], v[134:135], v[204:205]
	v_pk_fma_f32 v[136:137], v[238:239], v[136:137], v[206:207]
	v_cvt_pk_bf16_f32 v134, v134, v135
	v_cvt_pk_bf16_f32 v135, v136, v137
	global_store_dwordx2 v1, v[134:135], s[4:5] offset:512
	v_pk_mul_f32 v[138:139], v[138:139], v[58:59] op_sel_hi:[1,0]
	v_pk_mul_f32 v[140:141], v[140:141], v[58:59] op_sel_hi:[1,0]
	v_pk_mul_f32 v[138:139], v[10:11], v[138:139]
	v_pk_mul_f32 v[140:141], v[12:13], v[140:141]
	v_pk_fma_f32 v[138:139], v[240:241], v[138:139], v[208:209]
	v_pk_fma_f32 v[140:141], v[242:243], v[140:141], v[210:211]
	v_cvt_pk_bf16_f32 v138, v138, v139
	v_cvt_pk_bf16_f32 v139, v140, v141
	global_store_dwordx2 v1, v[138:139], s[4:5] offset:1024
	v_pk_mul_f32 v[142:143], v[142:143], v[58:59] op_sel_hi:[1,0]
	v_pk_mul_f32 v[144:145], v[144:145], v[58:59] op_sel_hi:[1,0]
	v_pk_mul_f32 v[142:143], v[14:15], v[142:143]
	v_pk_mul_f32 v[144:145], v[16:17], v[144:145]
	v_pk_fma_f32 v[142:143], v[244:245], v[142:143], v[212:213]
	v_pk_fma_f32 v[144:145], v[246:247], v[144:145], v[214:215]
	v_cvt_pk_bf16_f32 v142, v142, v143
	v_cvt_pk_bf16_f32 v143, v144, v145
	global_store_dwordx2 v1, v[142:143], s[4:5] offset:1536
	s_waitcnt vmcnt(4)
	v_pk_add_f32 v[34:35], v[34:35], 1.0 op_sel_hi:[1,0]
	v_pk_add_f32 v[36:37], v[36:37], 1.0 op_sel_hi:[1,0]
	v_pk_add_f32 v[38:39], v[38:39], 1.0 op_sel_hi:[1,0]
	v_pk_add_f32 v[40:41], v[40:41], 1.0 op_sel_hi:[1,0]
	v_pk_add_f32 v[42:43], v[42:43], 1.0 op_sel_hi:[1,0]
	v_pk_add_f32 v[44:45], v[44:45], 1.0 op_sel_hi:[1,0]
	v_pk_add_f32 v[46:47], v[46:47], 1.0 op_sel_hi:[1,0]
	v_pk_add_f32 v[48:49], v[48:49], 1.0 op_sel_hi:[1,0]
	s_add_u32 s4, s88, s25
	s_addc_u32 s5, s89, 0
	s_add_u32 s4, s4, 0x1400000
	s_addc_u32 s5, s5, 0
	v_pk_mul_f32 v[146:147], v[146:147], v[60:61] op_sel_hi:[1,0]
	v_pk_mul_f32 v[148:149], v[148:149], v[60:61] op_sel_hi:[1,0]
	v_pk_mul_f32 v[146:147], v[2:3], v[146:147]
	v_pk_mul_f32 v[148:149], v[4:5], v[148:149]
	v_pk_fma_f32 v[146:147], v[34:35], v[146:147], v[18:19]
	v_pk_fma_f32 v[148:149], v[36:37], v[148:149], v[20:21]
	v_cvt_pk_bf16_f32 v146, v146, v147
	v_cvt_pk_bf16_f32 v147, v148, v149
	global_store_dwordx2 v1, v[146:147], s[4:5]
	v_pk_mul_f32 v[150:151], v[150:151], v[60:61] op_sel_hi:[1,0]
	v_pk_mul_f32 v[152:153], v[152:153], v[60:61] op_sel_hi:[1,0]
	v_pk_mul_f32 v[150:151], v[6:7], v[150:151]
	v_pk_mul_f32 v[152:153], v[8:9], v[152:153]
	v_pk_fma_f32 v[150:151], v[38:39], v[150:151], v[22:23]
	v_pk_fma_f32 v[152:153], v[40:41], v[152:153], v[24:25]
	v_cvt_pk_bf16_f32 v150, v150, v151
	v_cvt_pk_bf16_f32 v151, v152, v153
	global_store_dwordx2 v1, v[150:151], s[4:5] offset:512
	v_pk_mul_f32 v[154:155], v[154:155], v[60:61] op_sel_hi:[1,0]
	v_pk_mul_f32 v[156:157], v[156:157], v[60:61] op_sel_hi:[1,0]
	v_pk_mul_f32 v[154:155], v[10:11], v[154:155]
	v_pk_mul_f32 v[156:157], v[12:13], v[156:157]
	v_pk_fma_f32 v[154:155], v[42:43], v[154:155], v[26:27]
	v_pk_fma_f32 v[156:157], v[44:45], v[156:157], v[28:29]
	v_cvt_pk_bf16_f32 v154, v154, v155
	v_cvt_pk_bf16_f32 v155, v156, v157
	global_store_dwordx2 v1, v[154:155], s[4:5] offset:1024
	v_pk_mul_f32 v[158:159], v[158:159], v[60:61] op_sel_hi:[1,0]
	v_pk_mul_f32 v[160:161], v[160:161], v[60:61] op_sel_hi:[1,0]
	v_pk_mul_f32 v[158:159], v[14:15], v[158:159]
	v_pk_mul_f32 v[160:161], v[16:17], v[160:161]
	v_pk_fma_f32 v[158:159], v[46:47], v[158:159], v[30:31]
	v_pk_fma_f32 v[160:161], v[48:49], v[160:161], v[32:33]
	v_cvt_pk_bf16_f32 v158, v158, v159
	v_cvt_pk_bf16_f32 v159, v160, v161
	global_store_dwordx2 v1, v[158:159], s[4:5] offset:1536
	s_branch .LBB0_539
